# idx top-k: packed clamp-FMA indicators (v_pk_fma_f32) feeding the MFMA count
# baseline (speedup 1.0000x reference)
.LBB0_820:
	s_waitcnt vmcnt(0) lgkmcnt(0)
	v_mov_b32_e32 v65, 0
	s_barrier
	s_lshl_b32 s26, s5, 1
	s_mov_b32 s36, 0xec800000
	s_mov_b32 s37, 0x6c800000
	s_mov_b32 s44, 0x6c800000
	v_mov_b32_e32 v149, 0xd1800000
	v_lshlrev_b32_e32 v152, 2, v197
	v_mov_b32_e32 v154, 0x3f803f80
	v_mov_b32_e32 v155, 0x3f803f80
	v_mov_b32_e32 v156, 0x3f803f80
	v_mov_b32_e32 v157, 0x3f803f80
	s_mov_b32 s4, 0

.Lsel_nosnap1:
	s_xor_b32 s1, s7, 0x80000000
	s_not_b32 s0, s7
	s_bitcmp1_b32 s7, 31
	s_cselect_b32 s0, s1, s0
	v_mov_b32_e32 v142, s0
	v_mul_f32_e32 v142, s37, v142
	v_pk_fma_f32 v[134:135], v[102:103], s[36:37], v[142:143] op_sel_hi:[1,0,0] clamp
	v_pk_fma_f32 v[136:137], v[104:105], s[36:37], v[142:143] op_sel_hi:[1,0,0] clamp
	v_pk_fma_f32 v[158:159], v[106:107], s[36:37], v[142:143] op_sel_hi:[1,0,0] clamp
	v_pk_fma_f32 v[160:161], v[108:109], s[36:37], v[142:143] op_sel_hi:[1,0,0] clamp
	v_mfma_f32_16x16x32_bf16 v[138:141], v[154:157], v[134:137], 0
	v_pk_fma_f32 v[134:135], v[110:111], s[36:37], v[142:143] op_sel_hi:[1,0,0] clamp
	v_pk_fma_f32 v[136:137], v[112:113], s[36:37], v[142:143] op_sel_hi:[1,0,0] clamp
	v_mfma_f32_16x16x32_bf16 v[138:141], v[154:157], v[158:161], v[138:141]
	v_pk_fma_f32 v[158:159], v[114:115], s[36:37], v[142:143] op_sel_hi:[1,0,0] clamp
	v_pk_fma_f32 v[160:161], v[116:117], s[36:37], v[142:143] op_sel_hi:[1,0,0] clamp
	v_mfma_f32_16x16x32_bf16 v[138:141], v[154:157], v[134:137], v[138:141]
	v_pk_fma_f32 v[134:135], v[118:119], s[36:37], v[142:143] op_sel_hi:[1,0,0] clamp
	v_pk_fma_f32 v[136:137], v[120:121], s[36:37], v[142:143] op_sel_hi:[1,0,0] clamp
	v_mfma_f32_16x16x32_bf16 v[138:141], v[154:157], v[158:161], v[138:141]
	v_pk_fma_f32 v[158:159], v[122:123], s[36:37], v[142:143] op_sel_hi:[1,0,0] clamp
	v_pk_fma_f32 v[160:161], v[124:125], s[36:37], v[142:143] op_sel_hi:[1,0,0] clamp
	v_mfma_f32_16x16x32_bf16 v[138:141], v[154:157], v[134:137], v[138:141]
	v_pk_fma_f32 v[134:135], v[126:127], s[36:37], v[142:143] op_sel_hi:[1,0,0] clamp
	v_pk_fma_f32 v[136:137], v[128:129], s[36:37], v[142:143] op_sel_hi:[1,0,0] clamp
	v_mfma_f32_16x16x32_bf16 v[138:141], v[154:157], v[158:161], v[138:141]
	v_pk_fma_f32 v[158:159], v[130:131], s[36:37], v[142:143] op_sel_hi:[1,0,0] clamp
	v_pk_fma_f32 v[160:161], v[132:133], s[36:37], v[142:143] op_sel_hi:[1,0,0] clamp
	v_mfma_f32_16x16x32_bf16 v[138:141], v[154:157], v[134:137], v[138:141]
	s_nop 0
	v_mfma_f32_16x16x32_bf16 v[138:141], v[154:157], v[158:161], v[138:141]
	s_nop 7
	v_add_f32_dpp v138, v138, v138 quad_perm:[1,0,3,2] row_mask:0xf bank_mask:0xf bound_ctrl:1
	s_nop 1
	v_add_f32_dpp v138, v138, v138 quad_perm:[2,3,0,1] row_mask:0xf bank_mask:0xf bound_ctrl:1
	s_nop 1
	v_add_f32_dpp v138, v138, v138 row_half_mirror row_mask:0xf bank_mask:0xf bound_ctrl:1
	s_nop 1
	v_add_f32_dpp v138, v138, v138 row_mirror row_mask:0xf bank_mask:0xf bound_ctrl:1
	v_cvt_u32_f32_e32 v138, v138
	s_nop 0
	v_readfirstlane_b32 s0, v138
	s_sub_i32 s0, 0x800, s0
	s_cmpk_lt_u32 s0, 0x100
	s_cbranch_scc1 .Lsel_bis_hi
	s_mov_b32 s29, s6
	s_mov_b32 s31, s0
	s_cmpk_eq_u32 s0, 0x100
	s_cbranch_scc0 .Lsel_bis
	s_branch .Lsel_bis_done

.Lsel_ties:
	v_mov_b32_e32 v150, s0
	v_mul_f32_e32 v142, s37, v150
	v_pk_fma_f32 v[134:135], v[102:103], s[44:45], v[142:143] op_sel_hi:[1,0,0] neg_lo:[0,0,1] neg_hi:[0,0,1] clamp
	v_pk_fma_f32 v[136:137], v[104:105], s[44:45], v[142:143] op_sel_hi:[1,0,0] neg_lo:[0,0,1] neg_hi:[0,0,1] clamp
	v_pk_fma_f32 v[158:159], v[106:107], s[44:45], v[142:143] op_sel_hi:[1,0,0] neg_lo:[0,0,1] neg_hi:[0,0,1] clamp
	v_pk_fma_f32 v[160:161], v[108:109], s[44:45], v[142:143] op_sel_hi:[1,0,0] neg_lo:[0,0,1] neg_hi:[0,0,1] clamp
	v_mfma_f32_16x16x32_bf16 v[138:141], v[154:157], v[134:137], 0
	v_pk_fma_f32 v[134:135], v[110:111], s[44:45], v[142:143] op_sel_hi:[1,0,0] neg_lo:[0,0,1] neg_hi:[0,0,1] clamp
	v_pk_fma_f32 v[136:137], v[112:113], s[44:45], v[142:143] op_sel_hi:[1,0,0] neg_lo:[0,0,1] neg_hi:[0,0,1] clamp
	v_mfma_f32_16x16x32_bf16 v[138:141], v[154:157], v[158:161], v[138:141]
	v_pk_fma_f32 v[158:159], v[114:115], s[44:45], v[142:143] op_sel_hi:[1,0,0] neg_lo:[0,0,1] neg_hi:[0,0,1] clamp
	v_pk_fma_f32 v[160:161], v[116:117], s[44:45], v[142:143] op_sel_hi:[1,0,0] neg_lo:[0,0,1] neg_hi:[0,0,1] clamp
	v_mfma_f32_16x16x32_bf16 v[138:141], v[154:157], v[134:137], v[138:141]
	v_pk_fma_f32 v[134:135], v[118:119], s[44:45], v[142:143] op_sel_hi:[1,0,0] neg_lo:[0,0,1] neg_hi:[0,0,1] clamp
	v_pk_fma_f32 v[136:137], v[120:121], s[44:45], v[142:143] op_sel_hi:[1,0,0] neg_lo:[0,0,1] neg_hi:[0,0,1] clamp
	v_mfma_f32_16x16x32_bf16 v[138:141], v[154:157], v[158:161], v[138:141]
	v_pk_fma_f32 v[158:159], v[122:123], s[44:45], v[142:143] op_sel_hi:[1,0,0] neg_lo:[0,0,1] neg_hi:[0,0,1] clamp
	v_pk_fma_f32 v[160:161], v[124:125], s[44:45], v[142:143] op_sel_hi:[1,0,0] neg_lo:[0,0,1] neg_hi:[0,0,1] clamp
	v_mfma_f32_16x16x32_bf16 v[138:141], v[154:157], v[134:137], v[138:141]
	v_pk_fma_f32 v[134:135], v[126:127], s[44:45], v[142:143] op_sel_hi:[1,0,0] neg_lo:[0,0,1] neg_hi:[0,0,1] clamp
	v_pk_fma_f32 v[136:137], v[128:129], s[44:45], v[142:143] op_sel_hi:[1,0,0] neg_lo:[0,0,1] neg_hi:[0,0,1] clamp
	v_mfma_f32_16x16x32_bf16 v[138:141], v[154:157], v[158:161], v[138:141]
	v_pk_fma_f32 v[158:159], v[130:131], s[44:45], v[142:143] op_sel_hi:[1,0,0] neg_lo:[0,0,1] neg_hi:[0,0,1] clamp
	v_pk_fma_f32 v[160:161], v[132:133], s[44:45], v[142:143] op_sel_hi:[1,0,0] neg_lo:[0,0,1] neg_hi:[0,0,1] clamp
	v_mfma_f32_16x16x32_bf16 v[138:141], v[154:157], v[134:137], v[138:141]
	s_nop 0
	v_mfma_f32_16x16x32_bf16 v[138:141], v[154:157], v[158:161], v[138:141]
	s_nop 7
	v_add_f32_dpp v138, v138, v138 quad_perm:[1,0,3,2] row_mask:0xf bank_mask:0xf bound_ctrl:1
	s_nop 1
	v_add_f32_dpp v138, v138, v138 quad_perm:[2,3,0,1] row_mask:0xf bank_mask:0xf bound_ctrl:1
	s_nop 1
	v_add_f32_dpp v138, v138, v138 row_half_mirror row_mask:0xf bank_mask:0xf bound_ctrl:1
	s_nop 1
	v_add_f32_dpp v138, v138, v138 row_mirror row_mask:0xf bank_mask:0xf bound_ctrl:1
	v_cvt_u32_f32_e32 v138, v138
	s_nop 0
	v_readfirstlane_b32 s0, v138
	s_sub_i32 s38, 0x100, s0
	s_mov_b32 s39, 0
	v_mov_b32_e32 v146, 0
	v_cmp_eq_f32_e64 s[42:43], v102, v150
	v_fma_f32 v134, v102, s37, -v142 clamp
	v_cvt_u32_f32_e32 v134, v134
	v_mbcnt_lo_u32_b32 v135, s42, 0
	v_mbcnt_hi_u32_b32 v135, s43, v135
	v_add_u32_e32 v135, s39, v135
	v_cmp_gt_u32_e32 vcc, s38, v135
	s_nop 1
	s_and_b64 vcc, vcc, s[42:43]
	s_nop 1
	v_cndmask_b32_e64 v136, 0, 1, vcc
	v_or_b32_e32 v136, v136, v134
	v_lshl_or_b32 v146, v136, 0, v146
	s_bcnt1_i32_b64 s0, s[42:43]
	s_add_i32 s39, s39, s0
	v_cmp_eq_f32_e64 s[42:43], v103, v150
	v_fma_f32 v134, v103, s37, -v142 clamp
	v_cvt_u32_f32_e32 v134, v134
	v_mbcnt_lo_u32_b32 v135, s42, 0
	v_mbcnt_hi_u32_b32 v135, s43, v135
	v_add_u32_e32 v135, s39, v135
	v_cmp_gt_u32_e32 vcc, s38, v135
	s_nop 1
	s_and_b64 vcc, vcc, s[42:43]
	s_nop 1
	v_cndmask_b32_e64 v136, 0, 1, vcc
	v_or_b32_e32 v136, v136, v134
	v_lshl_or_b32 v146, v136, 1, v146
	s_bcnt1_i32_b64 s0, s[42:43]
	s_add_i32 s39, s39, s0
	v_cmp_eq_f32_e64 s[42:43], v104, v150
	v_fma_f32 v134, v104, s37, -v142 clamp
	v_cvt_u32_f32_e32 v134, v134
	v_mbcnt_lo_u32_b32 v135, s42, 0
	v_mbcnt_hi_u32_b32 v135, s43, v135
	v_add_u32_e32 v135, s39, v135
	v_cmp_gt_u32_e32 vcc, s38, v135
	s_nop 1
	s_and_b64 vcc, vcc, s[42:43]
	s_nop 1
	v_cndmask_b32_e64 v136, 0, 1, vcc
	v_or_b32_e32 v136, v136, v134
	v_lshl_or_b32 v146, v136, 2, v146
	s_bcnt1_i32_b64 s0, s[42:43]
	s_add_i32 s39, s39, s0
	v_cmp_eq_f32_e64 s[42:43], v105, v150
	v_fma_f32 v134, v105, s37, -v142 clamp
	v_cvt_u32_f32_e32 v134, v134
	v_mbcnt_lo_u32_b32 v135, s42, 0
	v_mbcnt_hi_u32_b32 v135, s43, v135
	v_add_u32_e32 v135, s39, v135
	v_cmp_gt_u32_e32 vcc, s38, v135
	s_nop 1
	s_and_b64 vcc, vcc, s[42:43]
	s_nop 1
	v_cndmask_b32_e64 v136, 0, 1, vcc
	v_or_b32_e32 v136, v136, v134
	v_lshl_or_b32 v146, v136, 3, v146
	s_bcnt1_i32_b64 s0, s[42:43]
	s_add_i32 s39, s39, s0
	v_cmp_eq_f32_e64 s[42:43], v106, v150
	v_fma_f32 v134, v106, s37, -v142 clamp
	v_cvt_u32_f32_e32 v134, v134
	v_mbcnt_lo_u32_b32 v135, s42, 0
	v_mbcnt_hi_u32_b32 v135, s43, v135
	v_add_u32_e32 v135, s39, v135
	v_cmp_gt_u32_e32 vcc, s38, v135
	s_nop 1
	s_and_b64 vcc, vcc, s[42:43]
	s_nop 1
	v_cndmask_b32_e64 v136, 0, 1, vcc
	v_or_b32_e32 v136, v136, v134
	v_lshl_or_b32 v146, v136, 4, v146
	s_bcnt1_i32_b64 s0, s[42:43]
	s_add_i32 s39, s39, s0
	v_cmp_eq_f32_e64 s[42:43], v107, v150
	v_fma_f32 v134, v107, s37, -v142 clamp
	v_cvt_u32_f32_e32 v134, v134
	v_mbcnt_lo_u32_b32 v135, s42, 0
	v_mbcnt_hi_u32_b32 v135, s43, v135
	v_add_u32_e32 v135, s39, v135
	v_cmp_gt_u32_e32 vcc, s38, v135
	s_nop 1
	s_and_b64 vcc, vcc, s[42:43]
	s_nop 1
	v_cndmask_b32_e64 v136, 0, 1, vcc
	v_or_b32_e32 v136, v136, v134
	v_lshl_or_b32 v146, v136, 5, v146
	s_bcnt1_i32_b64 s0, s[42:43]
	s_add_i32 s39, s39, s0
	v_cmp_eq_f32_e64 s[42:43], v108, v150
	v_fma_f32 v134, v108, s37, -v142 clamp
	v_cvt_u32_f32_e32 v134, v134
	v_mbcnt_lo_u32_b32 v135, s42, 0
	v_mbcnt_hi_u32_b32 v135, s43, v135
	v_add_u32_e32 v135, s39, v135
	v_cmp_gt_u32_e32 vcc, s38, v135
	s_nop 1
	s_and_b64 vcc, vcc, s[42:43]
	s_nop 1
	v_cndmask_b32_e64 v136, 0, 1, vcc
	v_or_b32_e32 v136, v136, v134
	v_lshl_or_b32 v146, v136, 6, v146
	s_bcnt1_i32_b64 s0, s[42:43]
	s_add_i32 s39, s39, s0
	v_cmp_eq_f32_e64 s[42:43], v109, v150
	v_fma_f32 v134, v109, s37, -v142 clamp
	v_cvt_u32_f32_e32 v134, v134
	v_mbcnt_lo_u32_b32 v135, s42, 0
	v_mbcnt_hi_u32_b32 v135, s43, v135
	v_add_u32_e32 v135, s39, v135
	v_cmp_gt_u32_e32 vcc, s38, v135
	s_nop 1
	s_and_b64 vcc, vcc, s[42:43]
	s_nop 1
	v_cndmask_b32_e64 v136, 0, 1, vcc
	v_or_b32_e32 v136, v136, v134
	v_lshl_or_b32 v146, v136, 7, v146
	s_bcnt1_i32_b64 s0, s[42:43]
	s_add_i32 s39, s39, s0
	v_cmp_eq_f32_e64 s[42:43], v110, v150
	v_fma_f32 v134, v110, s37, -v142 clamp
	v_cvt_u32_f32_e32 v134, v134
	v_mbcnt_lo_u32_b32 v135, s42, 0
	v_mbcnt_hi_u32_b32 v135, s43, v135
	v_add_u32_e32 v135, s39, v135
	v_cmp_gt_u32_e32 vcc, s38, v135
	s_nop 1
	s_and_b64 vcc, vcc, s[42:43]
	s_nop 1
	v_cndmask_b32_e64 v136, 0, 1, vcc
	v_or_b32_e32 v136, v136, v134
	v_lshl_or_b32 v146, v136, 8, v146
	s_bcnt1_i32_b64 s0, s[42:43]
	s_add_i32 s39, s39, s0
	v_cmp_eq_f32_e64 s[42:43], v111, v150
	v_fma_f32 v134, v111, s37, -v142 clamp
	v_cvt_u32_f32_e32 v134, v134
	v_mbcnt_lo_u32_b32 v135, s42, 0
	v_mbcnt_hi_u32_b32 v135, s43, v135
	v_add_u32_e32 v135, s39, v135
	v_cmp_gt_u32_e32 vcc, s38, v135
	s_nop 1
	s_and_b64 vcc, vcc, s[42:43]
	s_nop 1
	v_cndmask_b32_e64 v136, 0, 1, vcc
	v_or_b32_e32 v136, v136, v134
	v_lshl_or_b32 v146, v136, 9, v146
	s_bcnt1_i32_b64 s0, s[42:43]
	s_add_i32 s39, s39, s0
	v_cmp_eq_f32_e64 s[42:43], v112, v150
	v_fma_f32 v134, v112, s37, -v142 clamp
	v_cvt_u32_f32_e32 v134, v134
	v_mbcnt_lo_u32_b32 v135, s42, 0
	v_mbcnt_hi_u32_b32 v135, s43, v135
	v_add_u32_e32 v135, s39, v135
	v_cmp_gt_u32_e32 vcc, s38, v135
	s_nop 1
	s_and_b64 vcc, vcc, s[42:43]
	s_nop 1
	v_cndmask_b32_e64 v136, 0, 1, vcc
	v_or_b32_e32 v136, v136, v134
	v_lshl_or_b32 v146, v136, 10, v146
	s_bcnt1_i32_b64 s0, s[42:43]
	s_add_i32 s39, s39, s0
	v_cmp_eq_f32_e64 s[42:43], v113, v150
	v_fma_f32 v134, v113, s37, -v142 clamp
	v_cvt_u32_f32_e32 v134, v134
	v_mbcnt_lo_u32_b32 v135, s42, 0
	v_mbcnt_hi_u32_b32 v135, s43, v135
	v_add_u32_e32 v135, s39, v135
	v_cmp_gt_u32_e32 vcc, s38, v135
	s_nop 1
	s_and_b64 vcc, vcc, s[42:43]
	s_nop 1
	v_cndmask_b32_e64 v136, 0, 1, vcc
	v_or_b32_e32 v136, v136, v134
	v_lshl_or_b32 v146, v136, 11, v146
	s_bcnt1_i32_b64 s0, s[42:43]
	s_add_i32 s39, s39, s0
	v_cmp_eq_f32_e64 s[42:43], v114, v150
	v_fma_f32 v134, v114, s37, -v142 clamp
	v_cvt_u32_f32_e32 v134, v134
	v_mbcnt_lo_u32_b32 v135, s42, 0
	v_mbcnt_hi_u32_b32 v135, s43, v135
	v_add_u32_e32 v135, s39, v135
	v_cmp_gt_u32_e32 vcc, s38, v135
	s_nop 1
	s_and_b64 vcc, vcc, s[42:43]
	s_nop 1
	v_cndmask_b32_e64 v136, 0, 1, vcc
	v_or_b32_e32 v136, v136, v134
	v_lshl_or_b32 v146, v136, 12, v146
	s_bcnt1_i32_b64 s0, s[42:43]
	s_add_i32 s39, s39, s0
	v_cmp_eq_f32_e64 s[42:43], v115, v150
	v_fma_f32 v134, v115, s37, -v142 clamp
	v_cvt_u32_f32_e32 v134, v134
	v_mbcnt_lo_u32_b32 v135, s42, 0
	v_mbcnt_hi_u32_b32 v135, s43, v135
	v_add_u32_e32 v135, s39, v135
	v_cmp_gt_u32_e32 vcc, s38, v135
	s_nop 1
	s_and_b64 vcc, vcc, s[42:43]
	s_nop 1
	v_cndmask_b32_e64 v136, 0, 1, vcc
	v_or_b32_e32 v136, v136, v134
	v_lshl_or_b32 v146, v136, 13, v146
	s_bcnt1_i32_b64 s0, s[42:43]
	s_add_i32 s39, s39, s0
	v_cmp_eq_f32_e64 s[42:43], v116, v150
	v_fma_f32 v134, v116, s37, -v142 clamp
	v_cvt_u32_f32_e32 v134, v134
	v_mbcnt_lo_u32_b32 v135, s42, 0
	v_mbcnt_hi_u32_b32 v135, s43, v135
	v_add_u32_e32 v135, s39, v135
	v_cmp_gt_u32_e32 vcc, s38, v135
	s_nop 1
	s_and_b64 vcc, vcc, s[42:43]
	s_nop 1
	v_cndmask_b32_e64 v136, 0, 1, vcc
	v_or_b32_e32 v136, v136, v134
	v_lshl_or_b32 v146, v136, 14, v146
	s_bcnt1_i32_b64 s0, s[42:43]
	s_add_i32 s39, s39, s0
	v_cmp_eq_f32_e64 s[42:43], v117, v150
	v_fma_f32 v134, v117, s37, -v142 clamp
	v_cvt_u32_f32_e32 v134, v134
	v_mbcnt_lo_u32_b32 v135, s42, 0
	v_mbcnt_hi_u32_b32 v135, s43, v135
	v_add_u32_e32 v135, s39, v135
	v_cmp_gt_u32_e32 vcc, s38, v135
	s_nop 1
	s_and_b64 vcc, vcc, s[42:43]
	s_nop 1
	v_cndmask_b32_e64 v136, 0, 1, vcc
	v_or_b32_e32 v136, v136, v134
	v_lshl_or_b32 v146, v136, 15, v146
	s_bcnt1_i32_b64 s0, s[42:43]
	s_add_i32 s39, s39, s0
	v_cmp_eq_f32_e64 s[42:43], v118, v150
	v_fma_f32 v134, v118, s37, -v142 clamp
	v_cvt_u32_f32_e32 v134, v134
	v_mbcnt_lo_u32_b32 v135, s42, 0
	v_mbcnt_hi_u32_b32 v135, s43, v135
	v_add_u32_e32 v135, s39, v135
	v_cmp_gt_u32_e32 vcc, s38, v135
	s_nop 1
	s_and_b64 vcc, vcc, s[42:43]
	s_nop 1
	v_cndmask_b32_e64 v136, 0, 1, vcc
	v_or_b32_e32 v136, v136, v134
	v_lshl_or_b32 v146, v136, 16, v146
	s_bcnt1_i32_b64 s0, s[42:43]
	s_add_i32 s39, s39, s0
	v_cmp_eq_f32_e64 s[42:43], v119, v150
	v_fma_f32 v134, v119, s37, -v142 clamp
	v_cvt_u32_f32_e32 v134, v134
	v_mbcnt_lo_u32_b32 v135, s42, 0
	v_mbcnt_hi_u32_b32 v135, s43, v135
	v_add_u32_e32 v135, s39, v135
	v_cmp_gt_u32_e32 vcc, s38, v135
	s_nop 1
	s_and_b64 vcc, vcc, s[42:43]
	s_nop 1
	v_cndmask_b32_e64 v136, 0, 1, vcc
	v_or_b32_e32 v136, v136, v134
	v_lshl_or_b32 v146, v136, 17, v146
	s_bcnt1_i32_b64 s0, s[42:43]
	s_add_i32 s39, s39, s0
	v_cmp_eq_f32_e64 s[42:43], v120, v150
	v_fma_f32 v134, v120, s37, -v142 clamp
	v_cvt_u32_f32_e32 v134, v134
	v_mbcnt_lo_u32_b32 v135, s42, 0
	v_mbcnt_hi_u32_b32 v135, s43, v135
	v_add_u32_e32 v135, s39, v135
	v_cmp_gt_u32_e32 vcc, s38, v135
	s_nop 1
	s_and_b64 vcc, vcc, s[42:43]
	s_nop 1
	v_cndmask_b32_e64 v136, 0, 1, vcc
	v_or_b32_e32 v136, v136, v134
	v_lshl_or_b32 v146, v136, 18, v146
	s_bcnt1_i32_b64 s0, s[42:43]
	s_add_i32 s39, s39, s0
	v_cmp_eq_f32_e64 s[42:43], v121, v150
	v_fma_f32 v134, v121, s37, -v142 clamp
	v_cvt_u32_f32_e32 v134, v134
	v_mbcnt_lo_u32_b32 v135, s42, 0
	v_mbcnt_hi_u32_b32 v135, s43, v135
	v_add_u32_e32 v135, s39, v135
	v_cmp_gt_u32_e32 vcc, s38, v135
	s_nop 1
	s_and_b64 vcc, vcc, s[42:43]
	s_nop 1
	v_cndmask_b32_e64 v136, 0, 1, vcc
	v_or_b32_e32 v136, v136, v134
	v_lshl_or_b32 v146, v136, 19, v146
	s_bcnt1_i32_b64 s0, s[42:43]
	s_add_i32 s39, s39, s0
	v_cmp_eq_f32_e64 s[42:43], v122, v150
	v_fma_f32 v134, v122, s37, -v142 clamp
	v_cvt_u32_f32_e32 v134, v134
	v_mbcnt_lo_u32_b32 v135, s42, 0
	v_mbcnt_hi_u32_b32 v135, s43, v135
	v_add_u32_e32 v135, s39, v135
	v_cmp_gt_u32_e32 vcc, s38, v135
	s_nop 1
	s_and_b64 vcc, vcc, s[42:43]
	s_nop 1
	v_cndmask_b32_e64 v136, 0, 1, vcc
	v_or_b32_e32 v136, v136, v134
	v_lshl_or_b32 v146, v136, 20, v146
	s_bcnt1_i32_b64 s0, s[42:43]
	s_add_i32 s39, s39, s0
	v_cmp_eq_f32_e64 s[42:43], v123, v150
	v_fma_f32 v134, v123, s37, -v142 clamp
	v_cvt_u32_f32_e32 v134, v134
	v_mbcnt_lo_u32_b32 v135, s42, 0
	v_mbcnt_hi_u32_b32 v135, s43, v135
	v_add_u32_e32 v135, s39, v135
	v_cmp_gt_u32_e32 vcc, s38, v135
	s_nop 1
	s_and_b64 vcc, vcc, s[42:43]
	s_nop 1
	v_cndmask_b32_e64 v136, 0, 1, vcc
	v_or_b32_e32 v136, v136, v134
	v_lshl_or_b32 v146, v136, 21, v146
	s_bcnt1_i32_b64 s0, s[42:43]
	s_add_i32 s39, s39, s0
	v_cmp_eq_f32_e64 s[42:43], v124, v150
	v_fma_f32 v134, v124, s37, -v142 clamp
	v_cvt_u32_f32_e32 v134, v134
	v_mbcnt_lo_u32_b32 v135, s42, 0
	v_mbcnt_hi_u32_b32 v135, s43, v135
	v_add_u32_e32 v135, s39, v135
	v_cmp_gt_u32_e32 vcc, s38, v135
	s_nop 1
	s_and_b64 vcc, vcc, s[42:43]
	s_nop 1
	v_cndmask_b32_e64 v136, 0, 1, vcc
	v_or_b32_e32 v136, v136, v134
	v_lshl_or_b32 v146, v136, 22, v146
	s_bcnt1_i32_b64 s0, s[42:43]
	s_add_i32 s39, s39, s0
	v_cmp_eq_f32_e64 s[42:43], v125, v150
	v_fma_f32 v134, v125, s37, -v142 clamp
	v_cvt_u32_f32_e32 v134, v134
	v_mbcnt_lo_u32_b32 v135, s42, 0
	v_mbcnt_hi_u32_b32 v135, s43, v135
	v_add_u32_e32 v135, s39, v135
	v_cmp_gt_u32_e32 vcc, s38, v135
	s_nop 1
	s_and_b64 vcc, vcc, s[42:43]
	s_nop 1
	v_cndmask_b32_e64 v136, 0, 1, vcc
	v_or_b32_e32 v136, v136, v134
	v_lshl_or_b32 v146, v136, 23, v146
	s_bcnt1_i32_b64 s0, s[42:43]
	s_add_i32 s39, s39, s0
	v_cmp_eq_f32_e64 s[42:43], v126, v150
	v_fma_f32 v134, v126, s37, -v142 clamp
	v_cvt_u32_f32_e32 v134, v134
	v_mbcnt_lo_u32_b32 v135, s42, 0
	v_mbcnt_hi_u32_b32 v135, s43, v135
	v_add_u32_e32 v135, s39, v135
	v_cmp_gt_u32_e32 vcc, s38, v135
	s_nop 1
	s_and_b64 vcc, vcc, s[42:43]
	s_nop 1
	v_cndmask_b32_e64 v136, 0, 1, vcc
	v_or_b32_e32 v136, v136, v134
	v_lshl_or_b32 v146, v136, 24, v146
	s_bcnt1_i32_b64 s0, s[42:43]
	s_add_i32 s39, s39, s0
	v_cmp_eq_f32_e64 s[42:43], v127, v150
	v_fma_f32 v134, v127, s37, -v142 clamp
	v_cvt_u32_f32_e32 v134, v134
	v_mbcnt_lo_u32_b32 v135, s42, 0
	v_mbcnt_hi_u32_b32 v135, s43, v135
	v_add_u32_e32 v135, s39, v135
	v_cmp_gt_u32_e32 vcc, s38, v135
	s_nop 1
	s_and_b64 vcc, vcc, s[42:43]
	s_nop 1
	v_cndmask_b32_e64 v136, 0, 1, vcc
	v_or_b32_e32 v136, v136, v134
	v_lshl_or_b32 v146, v136, 25, v146
	s_bcnt1_i32_b64 s0, s[42:43]
	s_add_i32 s39, s39, s0
	v_cmp_eq_f32_e64 s[42:43], v128, v150
	v_fma_f32 v134, v128, s37, -v142 clamp
	v_cvt_u32_f32_e32 v134, v134
	v_mbcnt_lo_u32_b32 v135, s42, 0
	v_mbcnt_hi_u32_b32 v135, s43, v135
	v_add_u32_e32 v135, s39, v135
	v_cmp_gt_u32_e32 vcc, s38, v135
	s_nop 1
	s_and_b64 vcc, vcc, s[42:43]
	s_nop 1
	v_cndmask_b32_e64 v136, 0, 1, vcc
	v_or_b32_e32 v136, v136, v134
	v_lshl_or_b32 v146, v136, 26, v146
	s_bcnt1_i32_b64 s0, s[42:43]
	s_add_i32 s39, s39, s0
	v_cmp_eq_f32_e64 s[42:43], v129, v150
	v_fma_f32 v134, v129, s37, -v142 clamp
	v_cvt_u32_f32_e32 v134, v134
	v_mbcnt_lo_u32_b32 v135, s42, 0
	v_mbcnt_hi_u32_b32 v135, s43, v135
	v_add_u32_e32 v135, s39, v135
	v_cmp_gt_u32_e32 vcc, s38, v135
	s_nop 1
	s_and_b64 vcc, vcc, s[42:43]
	s_nop 1
	v_cndmask_b32_e64 v136, 0, 1, vcc
	v_or_b32_e32 v136, v136, v134
	v_lshl_or_b32 v146, v136, 27, v146
	s_bcnt1_i32_b64 s0, s[42:43]
	s_add_i32 s39, s39, s0
	v_cmp_eq_f32_e64 s[42:43], v130, v150
	v_fma_f32 v134, v130, s37, -v142 clamp
	v_cvt_u32_f32_e32 v134, v134
	v_mbcnt_lo_u32_b32 v135, s42, 0
	v_mbcnt_hi_u32_b32 v135, s43, v135
	v_add_u32_e32 v135, s39, v135
	v_cmp_gt_u32_e32 vcc, s38, v135
	s_nop 1
	s_and_b64 vcc, vcc, s[42:43]
	s_nop 1
	v_cndmask_b32_e64 v136, 0, 1, vcc
	v_or_b32_e32 v136, v136, v134
	v_lshl_or_b32 v146, v136, 28, v146
	s_bcnt1_i32_b64 s0, s[42:43]
	s_add_i32 s39, s39, s0
	v_cmp_eq_f32_e64 s[42:43], v131, v150
	v_fma_f32 v134, v131, s37, -v142 clamp
	v_cvt_u32_f32_e32 v134, v134
	v_mbcnt_lo_u32_b32 v135, s42, 0
	v_mbcnt_hi_u32_b32 v135, s43, v135
	v_add_u32_e32 v135, s39, v135
	v_cmp_gt_u32_e32 vcc, s38, v135
	s_nop 1
	s_and_b64 vcc, vcc, s[42:43]
	s_nop 1
	v_cndmask_b32_e64 v136, 0, 1, vcc
	v_or_b32_e32 v136, v136, v134
	v_lshl_or_b32 v146, v136, 29, v146
	s_bcnt1_i32_b64 s0, s[42:43]
	s_add_i32 s39, s39, s0
	v_cmp_eq_f32_e64 s[42:43], v132, v150
	v_fma_f32 v134, v132, s37, -v142 clamp
	v_cvt_u32_f32_e32 v134, v134
	v_mbcnt_lo_u32_b32 v135, s42, 0
	v_mbcnt_hi_u32_b32 v135, s43, v135
	v_add_u32_e32 v135, s39, v135
	v_cmp_gt_u32_e32 vcc, s38, v135
	s_nop 1
	s_and_b64 vcc, vcc, s[42:43]
	s_nop 1
	v_cndmask_b32_e64 v136, 0, 1, vcc
	v_or_b32_e32 v136, v136, v134
	v_lshl_or_b32 v146, v136, 30, v146
	s_bcnt1_i32_b64 s0, s[42:43]
	s_add_i32 s39, s39, s0
	v_cmp_eq_f32_e64 s[42:43], v133, v150
	v_fma_f32 v134, v133, s37, -v142 clamp
	v_cvt_u32_f32_e32 v134, v134
	v_mbcnt_lo_u32_b32 v135, s42, 0
	v_mbcnt_hi_u32_b32 v135, s43, v135
	v_add_u32_e32 v135, s39, v135
	v_cmp_gt_u32_e32 vcc, s38, v135
	s_nop 1
	s_and_b64 vcc, vcc, s[42:43]
	s_nop 1
	v_cndmask_b32_e64 v136, 0, 1, vcc
	v_or_b32_e32 v136, v136, v134
	v_lshl_or_b32 v146, v136, 31, v146
	s_bcnt1_i32_b64 s0, s[42:43]
	s_add_i32 s39, s39, s0
	s_branch .Lsel_store
